# S5 sample items: waves 4-7 start ~1us later (s_sleep 38) so one wave's VALU overlaps its SIMD partner's load wait (stagger), on top of the output-stage stagger
# baseline (speedup 1.0000x reference)
; __device__ __forceinline__ float bf1(bf16 h) { return __uint_as_float((unsigned)h << 16); }
; #define GPTR(T, p) gptr_<T>(p)
; #define GIN(i) GPTR(const float, args.in[i])
; __device__ __forceinline__ void s5_sample_wave(int lane, int b, int g, const float* tb, const float* cre, const float* cim, const float* dsk,
;                                                const bf16* US, bf16* YS, const float* st_re, const float* st_im, float* out_re, float* out_im) {
;     ...
;     float hr = st_re[(size_t)(b * NG + g) * NP + p], hi = st_im[(size_t)(b * NG + g) * NP + p];
;     const int ho = ((lane >> 5) & 1) * 8 + ((lane >> 4) & 1) * 4 + ((lane >> 3) & 1) * 2 + ((lane >> 2) & 1);
;     const bf16* up0 = US + ((size_t)g * M + MP + (size_t)b * DECS) * 16;
;     v4u qa[DECS], qb[DECS]; float uho[DECS];
; #pragma unroll
;     for (int j = 0; j < DECS; ++j) { qa[j] = *(const v4u*)(up0 + 16 * j); qb[j] = *(const v4u*)(up0 + 16 * j + 8); uho[j] = bf1(up0[16 * j + ho]); }
;     const float dkh = dsk[g * 16 + ho];
; __global__ void __launch_bounds__(NWAVES * 64, 2) hymba_fwd(Args args) {
;     ...
;             for (int it = bx * NWAVES + wave; it < DECB * NG; it += G * NWAVES) { const int g = it & 31, b = it >> 5;
;                 s5_sample_wave(lane, b, g, tb, cre, cim, dsk, US, YS, GIN(I_STRE) + (size_t)L * DECB * NG * NP, GIN(I_STIM) + (size_t)L * DECB * NG * NP,
;                                GPTR(float, args.out) + O_RES + (size_t)L * DECB * NG * NP, GPTR(float, args.out) + O_IMS + (size_t)L * DECB * NG * NP); }
.LBB0_890:
	v_readlane_b32 s61, v254, 12
	s_add_i32 s2, s56, s61
	v_readlane_b32 s64, v254, 9
	v_readlane_b32 s72, v254, 38
	v_readlane_b32 s78, v254, 17
	v_readlane_b32 s80, v254, 21
	v_readlane_b32 s88, v255, 6
	v_readlane_b32 s92, v255, 8
	s_cmpk_gt_i32 s2, 0xfff
	v_readlane_b32 s65, v254, 10
	v_readlane_b32 s73, v254, 39
	v_readlane_b32 s76, v254, 40
	v_readlane_b32 s79, v254, 18
	v_readlane_b32 s81, v254, 22
	v_readlane_b32 s82, v254, 25
	v_readlane_b32 s83, v255, 5
	v_readlane_b32 s89, v255, 7
	v_readlane_b32 s93, v255, 9
	v_readlane_b32 s77, v254, 41
	s_cbranch_scc1 .LBB0_901
	v_readlane_b32 s0, v255, 3
	v_readlane_b32 s4, v254, 5
	v_readlane_b32 s1, v255, 4
	v_readlane_b32 s5, v254, 6
	s_add_u32 s18, s4, s0
	s_addc_u32 s19, s5, s1
	v_readlane_b32 s4, v254, 3
	v_readlane_b32 s5, v254, 4
	s_add_u32 s20, s4, s0
	v_and_b32_e32 v2, 16, v192
	s_addc_u32 s21, s5, s1
	v_cmp_eq_u32_e64 s[4:5], 0, v2
	v_and_b32_e32 v2, 8, v192
	s_ashr_i32 s3, s2, 31
	v_cmp_eq_u32_e64 s[6:7], 0, v2
	v_and_b32_e32 v2, 4, v192
	s_lshl_b64 s[12:13], s[2:3], 8
	v_readlane_b32 s14, v254, 63
	v_lshrrev_b32_e32 v44, 2, v196
	v_cmp_eq_u32_e64 s[8:9], 0, v2
	v_and_b32_e32 v2, 3, v192
	v_readlane_b32 s15, v255, 0
	s_add_u32 s12, s14, s12
	v_cmp_eq_u32_e64 s[10:11], 0, v2
	v_lshlrev_b32_e32 v2, 1, v44
	s_addc_u32 s13, s15, s13
	v_lshlrev_b32_e32 v48, 2, v196
	v_mov_b32_e32 v49, v3
	v_cmp_gt_u32_e64 s[0:1], 32, v196
	v_lshl_add_u64 v[46:47], s[22:23], 0, v[2:3]
	v_lshl_add_u64 v[50:51], s[12:13], 0, v[48:49]
	v_readfirstlane_b32 s99, v192
	s_nop 3
	s_lshr_b32 s99, s99, 6
	s_cmp_lt_u32 s99, 4
	s_cbranch_scc1 .Lsmp_stag
	s_sleep 38
.Lsmp_stag:
	s_waitcnt vmcnt(0)
	s_branch .LBB0_893
